# mLSTM chunk loop: end-of-chunk workgroup barrier removed; wave 0 now publishes the gated-value row 32 and the state-decay scalar after the first barrier of the chunk, so nothing the previous chunk's s
# speedup vs baseline: 1.1619x; 1.0061x over previous
; __device__ __forceinline__ void mlstm_task(const Ctx& c, int p, int l, int q, int h, int slab) {
;     ...
;         if (tid == 0) misc[0] = misc[2];
;         __syncthreads();
;     }
.LBB0_1583:
	s_or_b64 exec, exec, s[68:69]
	s_add_i32 s96, s96, 64
	s_add_i32 s75, s75, 1
	s_cmpk_eq_i32 s96, 0x2000
	s_waitcnt lgkmcnt(0)
	s_cbranch_scc1 .LBB0_1670

; __device__ __forceinline__ bf16_t f2bf(float f) { unsigned u = __float_as_uint(f); u += 0x7FFFu + ((u >> 16) & 1u); return (bf16_t)(u >> 16); }
; __device__ __forceinline__ void mlstm_task(const Ctx& c, int p, int l, int q, int h, int slab) {
;     ...
;         if (w == 0) {
;             const int t = lane; float ig = -1e30f, lf = 0.f;
;             if (t < nvalid) { ig = pgi + bi; const float gf = pgf + bf; lf = fminf(gf, 0.f) - __logf(1.0f + __expf(-fabsf(gf))); }
;             float bc = lf;
; #pragma unroll
;             for (int o = 1; o < 64; o <<= 1) { const float u = __shfl_up(bc, o); if (lane >= o) bc += u; }
;             float cm = ig - bc;
; #pragma unroll
;             for (int o = 1; o < 64; o <<= 1) { const float u = __shfl_up(cm, o); if (lane >= o) cm = fmaxf(cm, u); }
;             const float mprev = misc[0];
;             const float mt = bc + fmaxf(mprev, cm);
;             const float wi = __expf(bc + mprev - mt);
;             const float bL = __shfl(bc, 63), mnew = __shfl(mt, 63);
;             const float gs_ = __expf(bL - bc + ig - mnew);
;             mts[t] = mt; wint[t] = wi; gsrc[t] = gs_; VgT[32 * 72 + t] = f2bf(gs_); esc[t] = __expf(cm - fmaxf(mprev, cm));
;             if (lane == 0) { misc[1] = __expf(bL + mprev - mnew); misc[2] = mnew; }
;         }
.LBB0_1588:
	s_or_b64 exec, exec, s[86:87]
	v_mov_b32_e32 v8, v1
	s_nop 1
	v_add_f32_dpp v8, v8, v8 row_shr:1 row_mask:0xf bank_mask:0xf
	s_nop 1
	v_add_f32_dpp v8, v8, v8 row_shr:2 row_mask:0xf bank_mask:0xf
	s_nop 1
	v_add_f32_dpp v8, v8, v8 row_shr:4 row_mask:0xf bank_mask:0xf
	s_nop 1
	v_add_f32_dpp v8, v8, v8 row_shr:8 row_mask:0xf bank_mask:0xf
	s_nop 1
	v_add_f32_dpp v8, v8, v8 row_bcast:15 row_mask:0xa bank_mask:0xf
	s_nop 1
	v_add_f32_dpp v8, v8, v8 row_bcast:31 row_mask:0xc bank_mask:0xf
	v_mov_b32_e32 v1, s0
	ds_read_b32 v1, v1
	v_sub_f32_e32 v4, v0, v8
	s_nop 1
	v_max_f32_dpp v4, v4, v4 row_shr:1 row_mask:0xf bank_mask:0xf
	s_nop 1
	v_max_f32_dpp v4, v4, v4 row_shr:2 row_mask:0xf bank_mask:0xf
	s_nop 1
	v_max_f32_dpp v4, v4, v4 row_shr:4 row_mask:0xf bank_mask:0xf
	s_nop 1
	v_max_f32_dpp v4, v4, v4 row_shr:8 row_mask:0xf bank_mask:0xf
	s_nop 1
	v_max_f32_dpp v4, v4, v4 row_bcast:15 row_mask:0xa bank_mask:0xf
	s_nop 1
	v_max_f32_dpp v4, v4, v4 row_bcast:31 row_mask:0xc bank_mask:0xf
	v_readlane_b32 s68, v8, 63
	s_waitcnt lgkmcnt(0)
	v_max_f32_e32 v2, v4, v4
	v_max_f32_e32 v3, v1, v1
	v_max_f32_e32 v5, v3, v2
	v_add_f32_e32 v6, v8, v5
	v_add_f32_e32 v2, v1, v8
	v_sub_f32_e32 v2, v2, v6
	v_mul_f32_e32 v2, 0x3fb8aa3b, v2
	v_exp_f32_e32 v7, v2
	v_readlane_b32 s69, v6, 63
	v_mov_b32_e32 v3, s68
	v_sub_f32_e32 v8, v3, v8
	v_add_f32_e32 v0, v0, v8
	v_mov_b32_e32 v2, s69
	v_sub_f32_e32 v0, v0, v2
	v_mul_f32_e32 v0, 0x3fb8aa3b, v0
	v_exp_f32_e32 v0, v0
	ds_write_b32 v126, v6
	ds_write_b32 v127, v7
	ds_write_b32 v128, v0
	v_bfe_u32 v6, v0, 16, 1
	v_add3_u32 v84, v0, v6, s1
	v_sub_f32_e32 v0, v4, v5
	v_mul_f32_e32 v0, 0x3fb8aa3b, v0
	v_exp_f32_e32 v0, v0
	ds_write_b32 v130, v0
	s_and_saveexec_b64 s[68:69], s[28:29]
	s_cbranch_execz .LBB0_1590
	v_add_f32_e32 v0, v1, v3
	v_sub_f32_e32 v0, v0, v2
	v_mul_f32_e32 v0, 0x3fb8aa3b, v0
	v_exp_f32_e32 v0, v0
	v_mov_b32_e32 v86, v2
	v_mov_b32_e32 v85, v0

; __device__ __forceinline__ bf16_t f2bf(float f) { unsigned u = __float_as_uint(f); u += 0x7FFFu + ((u >> 16) & 1u); return (bf16_t)(u >> 16); }
; __device__ __forceinline__ void mlstm_task(const Ctx& c, int p, int l, int q, int h, int slab) {
;     ...
;             mts[t] = mt; wint[t] = wi; gsrc[t] = gs_; VgT[32 * 72 + t] = f2bf(gs_); esc[t] = __expf(cm - fmaxf(mprev, cm));
;             if (lane == 0) { misc[1] = __expf(bL + mprev - mnew); misc[2] = mnew; }
.LBB0_1629:
	s_andn2_b64 vcc, exec, s[76:77]
	s_cbranch_vccnz .Lml_def_skip
	ds_write_b16_d16_hi v129, v84 offset:4608
	s_and_saveexec_b64 s[68:69], s[28:29]
	v_mov_b32_e32 v1, s93
	ds_write2_b32 v1, v85, v86 offset1:1
	s_or_b64 exec, exec, s[68:69]
